# MLA tile loop: K/V/k_pe tile loads issued two tiles ahead into a second register set selected by the LDS buffer parity (was one tile ahead, waited with vmcnt(0) at the end of the tile)
# baseline (speedup 1.0000x reference)
; DEVI void mla_item(const Ctx& cx, int b, int h, int qt, unsigned char* lds, int wv) {
;     ...
;   const int ntiles = 4 * qt + 4;
;   u32x4 kr, vr, pr;
;   auto gload = [&](int m) {
;     kr = *(const u32x4*)(cx.kn + ((size_t)(b * S + m * 64 + lr)) * 320 + h * 64 + lc * 8);
;     vr = *(const u32x4*)(cx.mlavT + ((size_t)((b * 5 + h) * 64 + lr)) * S + m * 64 + lc * 8);
;     if (tid < 256) pr = *(const u32x4*)(cx.proj + ((size_t)(b * S + m * 64 + lr2)) * PS + C_KPE + lc2 * 8);
;   };
;   auto lwrite = [&](int bi) {
;     *(u32x4*)(lds + ATT_K0 + bi * ATT_KSZ + lr * KROW_MLA + lc * 16) = kr;
;     *(u32x4*)(lds + ATT_V0 + bi * ATT_VSZ + lr * LDS_ROW + lc * 16) = vr;
;     if (tid < 256) *(u32x4*)(lds + ATT_K0 + bi * ATT_KSZ + lr2 * KROW_MLA + 128 + lc2 * 16) = pr;
;   };
;   gload(0); lwrite(0);
;   __syncthreads();
;   int bi = 0;
.LBB0_1356:
	s_or_b64 exec, exec, s[6:7]
	s_movk_i32 s6, 0xd0
	v_mul_lo_u32 v112, v42, s6
	v_add3_u32 v32, 0, v112, v90
	v_lshlrev_b32_e32 v48, 6, v42
	v_sub_u32_e32 v113, v32, v48
	s_waitcnt vmcnt(1)
	ds_write_b128 v32, v[24:27]
	s_waitcnt vmcnt(0)
	ds_write_b128 v113, v[28:31] offset:26624
	s_and_saveexec_b64 s[6:7], vcc
	s_xor_b64 s[6:7], exec, s[6:7]
	v_lshlrev_b32_e32 v114, 4, v47
	s_or_saveexec_b64 s[6:7], s[6:7]
	v_mul_u32_u24_e32 v116, 0xd0, v45
	s_xor_b64 exec, exec, s[6:7]
	v_add3_u32 v32, 0, v116, v40
	v_mov_b32_e32 v114, v40
	ds_write_b128 v32, v[34:37] offset:128
	s_or_b64 exec, exec, s[6:7]
	v_lshlrev_b32_e32 v32, 3, v44
	v_lshl_add_u32 v47, v44, 4, 0
	s_movk_i32 s6, 0xd0
	v_mad_u32_u24 v118, v41, s6, v47
	v_sub_u32_e32 v32, v47, v32
	s_movk_i32 s6, 0x90
	v_mad_u32_u24 v119, v41, s6, v32
	s_lshl_b64 s[6:7], s[4:5], 1
	v_readlane_b32 s4, v253, 28
	v_lshlrev_b32_e32 v46, 3, v46
	v_readlane_b32 s5, v253, 29
	s_add_u32 s4, s4, s6
	s_addc_u32 s5, s5, s7
	v_lshlrev_b32_e32 v32, 1, v46
	v_readlane_b32 s20, v252, 40
	v_lshl_add_u64 v[94:95], s[4:5], 0, v[32:33]
	v_mov_b32_e32 v41, v33
	v_readlane_b32 s22, v252, 42
	v_readlane_b32 s23, v252, 43
	v_mov_b32_e32 v91, v33
	v_readlane_b32 s4, v254, 46
	v_lshlrev_b32_e32 v43, 2, v43
	v_lshl_add_u64 v[96:97], s[22:23], 0, v[40:41]
	v_lshl_add_u64 v[38:39], v[38:39], 0, v[90:91]
	v_readlane_b32 s5, v254, 47
	s_add_i32 s8, s8, 64
	v_mov_b32_e32 v40, v33
	v_lshlrev_b32_e32 v115, 2, v44
	v_bitop3_b32 v110, v43, s58, v237 bitop3:0x6c
	v_lshl_add_u64 v[98:99], s[4:5], 0, v[38:39]
	v_add_u32_e32 v91, s8, v45
	v_add_u32_e32 v122, s8, v42
	v_mov_b32_e32 v131, v130
	v_mov_b32_e32 v32, v33
	v_mov_b32_e32 v38, v33
	v_mov_b32_e32 v39, v33
	v_mov_b64_e32 v[44:45], v[40:41]
	v_mov_b64_e32 v[48:49], v[40:41]
	v_mov_b64_e32 v[52:53], v[40:41]
	v_mov_b64_e32 v[56:57], v[40:41]
	v_mov_b64_e32 v[60:61], v[40:41]
	v_mov_b64_e32 v[64:65], v[40:41]
	v_mov_b64_e32 v[68:69], v[40:41]
	v_or_b32_e32 v117, 31, v108
	v_add_u32_e32 v120, 14, v109
	v_add_u32_e32 v121, 13, v109
	s_mov_b32 s16, 1
	s_mov_b32 s17, 0
	v_mov_b64_e32 v[42:43], v[38:39]
	v_mov_b64_e32 v[46:47], v[38:39]
	v_mov_b64_e32 v[50:51], v[38:39]
	v_mov_b64_e32 v[54:55], v[38:39]
	v_mov_b64_e32 v[58:59], v[38:39]
	v_mov_b64_e32 v[62:63], v[38:39]
	v_mov_b64_e32 v[66:67], v[38:39]
	s_mov_b32 s18, 0
	v_mov_b64_e32 v[92:93], v[32:33]
	v_mov_b64_e32 v[100:101], v[130:131]
	v_add_u32_e32 v194, s17, v122
	v_mad_i64_i32 v[194:195], s[4:5], v194, s60, v[94:95]
	global_load_dwordx4 v[194:197], v[194:195], off
	s_nop 0
	global_load_dwordx4 v[198:201], v[98:99], off
	s_and_saveexec_b64 s[4:5], s[0:1]
	s_cbranch_execz .Lmla_pro_skip
	v_add_u32_e32 v32, s17, v91
	v_mad_i64_i32 v[202:203], s[10:11], v32, s33, v[96:97]
	global_load_dwordx4 v[202:205], v[202:203], off offset:2624
.Lmla_pro_skip:
	s_or_b64 exec, exec, s[4:5]
	s_waitcnt lgkmcnt(0)
	s_barrier
	v_readlane_b32 s21, v252, 41
	s_branch .LBB0_1363

; DEVI void mla_item(const Ctx& cx, int b, int h, int qt, unsigned char* lds, int wv) {
;     ...
;   auto gload = [&](int m) {
;     kr = *(const u32x4*)(cx.kn + ((size_t)(b * S + m * 64 + lr)) * 320 + h * 64 + lc * 8);
;     vr = *(const u32x4*)(cx.mlavT + ((size_t)((b * 5 + h) * 64 + lr)) * S + m * 64 + lc * 8);
;     if (tid < 256) pr = *(const u32x4*)(cx.proj + ((size_t)(b * S + m * 64 + lr2)) * PS + C_KPE + lc2 * 8);
;   };
;     ...
; #pragma unroll 1
;   for (int m = 0; m < ntiles; ++m) {
;     if (m + 1 < ntiles) gload(m + 1);
.LBB0_1363:
	s_cmp_lt_u32 s16, s15
	s_cselect_b64 s[8:9], -1, 0
	s_add_i32 s4, s16, 1
	s_cmp_ge_u32 s4, s15
	s_cbranch_scc1 .LBB0_1368
	s_cmp_lg_u32 s18, 0
	s_cbranch_scc1 .Lmla_glB
	v_add_u32_e32 v24, s17, v122
	v_add_u32_e32 v24, 64, v24
	v_mad_i64_i32 v[24:25], s[4:5], v24, s60, v[94:95]
	global_load_dwordx4 v[24:27], v[24:25], off
	s_nop 0
	global_load_dwordx4 v[28:31], v[98:99], off offset:128
	s_and_saveexec_b64 s[4:5], s[0:1]
	s_cbranch_execz .LBB0_1366
	v_add_u32_e32 v32, s17, v91
	v_add_u32_e32 v32, 64, v32
	v_mad_i64_i32 v[34:35], s[10:11], v32, s33, v[96:97]
	global_load_dwordx4 v[34:37], v[34:35], off offset:2624
	s_branch .LBB0_1366
.Lmla_glB:
	v_add_u32_e32 v194, s17, v122
	v_add_u32_e32 v194, 64, v194
	v_mad_i64_i32 v[194:195], s[4:5], v194, s60, v[94:95]
	global_load_dwordx4 v[194:197], v[194:195], off
	s_nop 0
	global_load_dwordx4 v[198:201], v[98:99], off offset:128
	s_and_saveexec_b64 s[4:5], s[0:1]
	s_cbranch_execz .LBB0_1366
	v_add_u32_e32 v32, s17, v91
	v_add_u32_e32 v32, 64, v32
	v_mad_i64_i32 v[202:203], s[10:11], v32, s33, v[96:97]
	global_load_dwordx4 v[202:205], v[202:203], off offset:2624

; DEVI void mla_item(const Ctx& cx, int b, int h, int qt, unsigned char* lds, int wv) {
;     ...
;   auto lwrite = [&](int bi) {
;     *(u32x4*)(lds + ATT_K0 + bi * ATT_KSZ + lr * KROW_MLA + lc * 16) = kr;
;     *(u32x4*)(lds + ATT_V0 + bi * ATT_VSZ + lr * LDS_ROW + lc * 16) = vr;
;     if (tid < 256) *(u32x4*)(lds + ATT_K0 + bi * ATT_KSZ + lr2 * KROW_MLA + 128 + lc2 * 16) = pr;
;   };
;     ...
;     if (m + 1 < ntiles) lwrite(bi ^ 1);
;     __syncthreads();
;     bi ^= 1;
.LBB0_1386:
	s_mul_i32 s4, s18, 0x3400
	s_add_i32 s8, s4, 0
	v_add3_u32 v32, s8, v112, v90
	s_mul_i32 s4, s18, 0x2400
	s_add_i32 s5, s16, 1
	s_cmp_lt_u32 s5, s15
	s_cbranch_scc1 .Lmla_w2
	s_waitcnt vmcnt(0)
	s_branch .Lmla_wd
.Lmla_w2:
	s_waitcnt vmcnt(2)
.Lmla_wd:
	s_cmp_lg_u32 s18, 0
	s_cbranch_scc1 .Lmla_lwB
	ds_write_b128 v32, v[24:27]
	v_add_u32_e32 v32, s4, v113
	ds_write_b128 v32, v[28:31] offset:26624
	s_and_saveexec_b64 s[4:5], s[0:1]
	s_cbranch_execz .LBB0_1361
	v_add3_u32 v32, s8, v116, v114
	ds_write_b128 v32, v[34:37] offset:128
	s_branch .LBB0_1361
.Lmla_lwB:
	ds_write_b128 v32, v[194:197]
	v_add_u32_e32 v32, s4, v113
	ds_write_b128 v32, v[198:201] offset:26624
	s_and_saveexec_b64 s[4:5], s[0:1]
	s_cbranch_execz .LBB0_1361
	v_add3_u32 v32, s8, v116, v114
	ds_write_b128 v32, v[202:205] offset:128
	s_branch .LBB0_1361
